# attention fast trip: LDS-DMA blocks write m0 directly with a neighbouring VALU as filler (no m0 save/restore/s_nop), always-satisfied phase-A lgkmcnt waits dropped
# baseline (speedup 1.0000x reference)
.Lfast3:
.Lf3_0_485:
	ds_read_b64_tr_b16 v[178:179], v203 offset:24576
	ds_read_b64_tr_b16 v[180:181], v203 offset:25088
	v_mfma_f32_32x32x16_bf16 v[98:113], v[174:177], v[142:145], v[34:49]
	v_add_f32_e32 v82, v66, v67
	v_add_f32_e32 v82, v68, v82
	v_add_f32_e32 v82, v69, v82
	v_add_f32_e32 v82, v70, v82
	v_add_f32_e32 v82, v71, v82
	v_cvt_pk_bf16_f32 v138, v66, v67
	v_cvt_pk_bf16_f32 v139, v68, v69
	ds_read_b64_tr_b16 v[174:175], v203 offset:28672
	ds_read_b64_tr_b16 v[176:177], v203 offset:29184
	v_add_f32_e32 v66, v72, v82
	v_mfma_f32_32x32x16_bf16 v[82:97], v[170:173], v[142:145], v[34:49]
	v_add_f32_e32 v66, v73, v66
	v_add_f32_e32 v66, v74, v66
	v_add_f32_e32 v114, v75, v66
	v_cvt_pk_bf16_f32 v140, v70, v71
	v_cvt_pk_bf16_f32 v141, v72, v73
	ds_read_b64_tr_b16 v[66:67], v203 offset:25600
	ds_read_b64_tr_b16 v[68:69], v203 offset:26112
	v_mfma_f32_32x32x16_bf16 v[98:113], v[166:169], v[134:137], v[98:113]
	v_add_f32_e32 v70, v76, v114
	v_add_f32_e32 v70, v77, v70
	v_add_f32_e32 v70, v78, v70
	v_add_f32_e32 v114, v79, v70
	v_cvt_pk_bf16_f32 v130, v74, v75
	v_cvt_pk_bf16_f32 v131, v76, v77
	ds_read_b64_tr_b16 v[70:71], v203 offset:29696
	ds_read_b64_tr_b16 v[72:73], v203 offset:30208
	v_mfma_f32_32x32x16_bf16 v[82:97], v[162:165], v[134:137], v[82:97]
	v_add_f32_e32 v74, v80, v114
	v_add_f32_e32 v74, v81, v74
	v_add_f32_e32 v74, v50, v74
	v_add_f32_e32 v114, v51, v74
	v_cvt_pk_bf16_f32 v132, v78, v79
	v_cvt_pk_bf16_f32 v133, v80, v81
	ds_read_b64_tr_b16 v[74:75], v203 offset:26624
	ds_read_b64_tr_b16 v[76:77], v203 offset:27136
	v_mfma_f32_32x32x16_bf16 v[98:113], v[158:161], v[126:129], v[98:113]
	v_add_f32_e32 v78, v52, v114
	v_add_f32_e32 v78, v53, v78
	v_add_f32_e32 v78, v54, v78
	v_add_f32_e32 v78, v55, v78
	v_cvt_pk_bf16_f32 v122, v50, v51
	v_cvt_pk_bf16_f32 v123, v52, v53
	ds_read_b64_tr_b16 v[50:51], v203 offset:30720
	ds_read_b64_tr_b16 v[52:53], v203 offset:31232
	v_mfma_f32_32x32x16_bf16 v[82:97], v[154:157], v[126:129], v[82:97]
	v_add_f32_e32 v78, v56, v78
	v_add_f32_e32 v78, v57, v78
	v_add_f32_e32 v78, v58, v78
	v_add_f32_e32 v78, v59, v78
	v_cvt_pk_bf16_f32 v124, v54, v55
	v_cvt_pk_bf16_f32 v125, v56, v57
	ds_read_b64_tr_b16 v[54:55], v203 offset:27648
	ds_read_b64_tr_b16 v[56:57], v203 offset:28160
	v_mfma_f32_32x32x16_bf16 v[98:113], v[150:153], v[118:121], v[98:113]
	v_add_f32_e32 v78, v60, v78
	v_add_f32_e32 v78, v61, v78
	v_add_f32_e32 v78, v62, v78
	v_add_f32_e32 v78, v63, v78
	v_cvt_pk_bf16_f32 v114, v58, v59
	v_cvt_pk_bf16_f32 v115, v60, v61
	ds_read_b64_tr_b16 v[58:59], v203 offset:31744
	ds_read_b64_tr_b16 v[60:61], v203 offset:32256
	v_mfma_f32_32x32x16_bf16 v[82:97], v[146:149], v[118:121], v[82:97]
	v_add_f32_e32 v78, v64, v78
	v_add_f32_e32 v78, v65, v78
	v_cvt_pk_bf16_f32 v116, v62, v63
	s_add_i32 m0, s46, 0x2000
	v_cvt_pk_bf16_f32 v117, v64, v65
	global_load_lds_dwordx4 v188, s[100:101]
	s_add_i32 m0, s47, 0x4000
	v_add_f32_e32 v190, v205, v78
	global_load_lds_dwordx4 v186, s[100:101]

.Lf3_0_488:
	ds_read_b64_tr_b16 v[150:151], v203 offset:32768
	ds_read_b64_tr_b16 v[152:153], v203 offset:33280
	v_mfma_f32_32x32x16_bf16 v[66:81], v[62:65], v[142:145], v[34:49]
	v_add_f32_e32 v50, v98, v99
	v_add_f32_e32 v50, v100, v50
	v_add_f32_e32 v50, v101, v50
	v_add_f32_e32 v50, v102, v50
	v_add_f32_e32 v50, v103, v50
	v_cvt_pk_bf16_f32 v138, v98, v99
	v_cvt_pk_bf16_f32 v139, v100, v101
	ds_read_b64_tr_b16 v[146:147], v203 offset:36864
	ds_read_b64_tr_b16 v[148:149], v203 offset:37376
	v_add_f32_e32 v50, v104, v50
	v_add_f32_e32 v50, v105, v50
	v_add_f32_e32 v50, v106, v50
	v_add_f32_e32 v114, v107, v50
	v_mfma_f32_32x32x16_bf16 v[50:65], v[174:177], v[142:145], v[34:49]
	v_cvt_pk_bf16_f32 v140, v102, v103
	v_cvt_pk_bf16_f32 v141, v104, v105
	ds_read_b64_tr_b16 v[98:99], v203 offset:33792
	ds_read_b64_tr_b16 v[100:101], v203 offset:34304
	v_mfma_f32_32x32x16_bf16 v[66:81], v[178:181], v[134:137], v[66:81]
	v_add_f32_e32 v102, v108, v114
	v_add_f32_e32 v102, v109, v102
	v_add_f32_e32 v102, v110, v102
	v_add_f32_e32 v114, v111, v102
	v_cvt_pk_bf16_f32 v130, v106, v107
	v_cvt_pk_bf16_f32 v131, v108, v109
	ds_read_b64_tr_b16 v[102:103], v203 offset:37888
	ds_read_b64_tr_b16 v[104:105], v203 offset:38400
	v_mfma_f32_32x32x16_bf16 v[50:65], v[170:173], v[134:137], v[50:65]
	v_add_f32_e32 v106, v112, v114
	v_add_f32_e32 v106, v113, v106
	v_add_f32_e32 v106, v82, v106
	v_add_f32_e32 v114, v83, v106
	v_cvt_pk_bf16_f32 v132, v110, v111
	v_cvt_pk_bf16_f32 v133, v112, v113
	ds_read_b64_tr_b16 v[106:107], v203 offset:34816
	ds_read_b64_tr_b16 v[108:109], v203 offset:35328
	v_mfma_f32_32x32x16_bf16 v[66:81], v[166:169], v[126:129], v[66:81]
	v_add_f32_e32 v110, v84, v114
	v_add_f32_e32 v110, v85, v110
	v_add_f32_e32 v110, v86, v110
	v_add_f32_e32 v110, v87, v110
	v_cvt_pk_bf16_f32 v122, v82, v83
	v_cvt_pk_bf16_f32 v123, v84, v85
	ds_read_b64_tr_b16 v[82:83], v203 offset:38912
	ds_read_b64_tr_b16 v[84:85], v203 offset:39424
	v_mfma_f32_32x32x16_bf16 v[50:65], v[162:165], v[126:129], v[50:65]
	v_add_f32_e32 v110, v88, v110
	v_add_f32_e32 v110, v89, v110
	v_add_f32_e32 v110, v90, v110
	v_add_f32_e32 v110, v91, v110
	v_cvt_pk_bf16_f32 v124, v86, v87
	v_cvt_pk_bf16_f32 v125, v88, v89
	ds_read_b64_tr_b16 v[86:87], v203 offset:35840
	ds_read_b64_tr_b16 v[88:89], v203 offset:36352
	v_mfma_f32_32x32x16_bf16 v[66:81], v[158:161], v[118:121], v[66:81]
	v_add_f32_e32 v110, v92, v110
	v_add_f32_e32 v110, v93, v110
	v_add_f32_e32 v110, v94, v110
	v_add_f32_e32 v110, v95, v110
	v_cvt_pk_bf16_f32 v114, v90, v91
	v_cvt_pk_bf16_f32 v115, v92, v93
	ds_read_b64_tr_b16 v[90:91], v203 offset:39936
	ds_read_b64_tr_b16 v[92:93], v203 offset:40448
	v_mfma_f32_32x32x16_bf16 v[50:65], v[154:157], v[118:121], v[50:65]
	v_add_f32_e32 v110, v96, v110
	v_add_f32_e32 v110, v97, v110
	v_cvt_pk_bf16_f32 v116, v94, v95
	s_add_i32 m0, s46, 0x4000
	v_cvt_pk_bf16_f32 v117, v96, v97
	global_load_lds_dwordx4 v189, s[100:101]
	s_add_i32 m0, s47, 0x0
	v_add_f32_e32 v205, v190, v110
	global_load_lds_dwordx4 v187, s[100:101]

.Lf3_1_485:
	ds_read_b64_tr_b16 v[178:179], v203 offset:40960
	ds_read_b64_tr_b16 v[180:181], v203 offset:41472
	v_mfma_f32_32x32x16_bf16 v[98:113], v[174:177], v[142:145], v[34:49]
	v_add_f32_e32 v82, v66, v67
	v_add_f32_e32 v82, v68, v82
	v_add_f32_e32 v82, v69, v82
	v_add_f32_e32 v82, v70, v82
	v_add_f32_e32 v82, v71, v82
	v_cvt_pk_bf16_f32 v138, v66, v67
	v_cvt_pk_bf16_f32 v139, v68, v69
	ds_read_b64_tr_b16 v[174:175], v203 offset:45056
	ds_read_b64_tr_b16 v[176:177], v203 offset:45568
	v_add_f32_e32 v66, v72, v82
	v_mfma_f32_32x32x16_bf16 v[82:97], v[170:173], v[142:145], v[34:49]
	v_add_f32_e32 v66, v73, v66
	v_add_f32_e32 v66, v74, v66
	v_add_f32_e32 v114, v75, v66
	v_cvt_pk_bf16_f32 v140, v70, v71
	v_cvt_pk_bf16_f32 v141, v72, v73
	ds_read_b64_tr_b16 v[66:67], v203 offset:41984
	ds_read_b64_tr_b16 v[68:69], v203 offset:42496
	v_mfma_f32_32x32x16_bf16 v[98:113], v[166:169], v[134:137], v[98:113]
	v_add_f32_e32 v70, v76, v114
	v_add_f32_e32 v70, v77, v70
	v_add_f32_e32 v70, v78, v70
	v_add_f32_e32 v114, v79, v70
	v_cvt_pk_bf16_f32 v130, v74, v75
	v_cvt_pk_bf16_f32 v131, v76, v77
	ds_read_b64_tr_b16 v[70:71], v203 offset:46080
	ds_read_b64_tr_b16 v[72:73], v203 offset:46592
	v_mfma_f32_32x32x16_bf16 v[82:97], v[162:165], v[134:137], v[82:97]
	v_add_f32_e32 v74, v80, v114
	v_add_f32_e32 v74, v81, v74
	v_add_f32_e32 v74, v50, v74
	v_add_f32_e32 v114, v51, v74
	v_cvt_pk_bf16_f32 v132, v78, v79
	v_cvt_pk_bf16_f32 v133, v80, v81
	ds_read_b64_tr_b16 v[74:75], v203 offset:43008
	ds_read_b64_tr_b16 v[76:77], v203 offset:43520
	v_mfma_f32_32x32x16_bf16 v[98:113], v[158:161], v[126:129], v[98:113]
	v_add_f32_e32 v78, v52, v114
	v_add_f32_e32 v78, v53, v78
	v_add_f32_e32 v78, v54, v78
	v_add_f32_e32 v78, v55, v78
	v_cvt_pk_bf16_f32 v122, v50, v51
	v_cvt_pk_bf16_f32 v123, v52, v53
	ds_read_b64_tr_b16 v[50:51], v203 offset:47104
	ds_read_b64_tr_b16 v[52:53], v203 offset:47616
	v_mfma_f32_32x32x16_bf16 v[82:97], v[154:157], v[126:129], v[82:97]
	v_add_f32_e32 v78, v56, v78
	v_add_f32_e32 v78, v57, v78
	v_add_f32_e32 v78, v58, v78
	v_add_f32_e32 v78, v59, v78
	v_cvt_pk_bf16_f32 v124, v54, v55
	v_cvt_pk_bf16_f32 v125, v56, v57
	ds_read_b64_tr_b16 v[54:55], v203 offset:44032
	ds_read_b64_tr_b16 v[56:57], v203 offset:44544
	v_mfma_f32_32x32x16_bf16 v[98:113], v[150:153], v[118:121], v[98:113]
	v_add_f32_e32 v78, v60, v78
	v_add_f32_e32 v78, v61, v78
	v_add_f32_e32 v78, v62, v78
	v_add_f32_e32 v78, v63, v78
	v_cvt_pk_bf16_f32 v114, v58, v59
	v_cvt_pk_bf16_f32 v115, v60, v61
	ds_read_b64_tr_b16 v[58:59], v203 offset:48128
	ds_read_b64_tr_b16 v[60:61], v203 offset:48640
	v_mfma_f32_32x32x16_bf16 v[82:97], v[146:149], v[118:121], v[82:97]
	v_add_f32_e32 v78, v64, v78
	v_add_f32_e32 v78, v65, v78
	v_cvt_pk_bf16_f32 v116, v62, v63
	s_add_i32 m0, s46, 0x0
	v_cvt_pk_bf16_f32 v117, v64, v65
	global_load_lds_dwordx4 v188, s[100:101]
	s_add_i32 m0, s47, 0x2000
	v_add_f32_e32 v190, v205, v78
	global_load_lds_dwordx4 v186, s[100:101]

.Lf3_1_488:
	ds_read_b64_tr_b16 v[150:151], v203 offset:24576
	ds_read_b64_tr_b16 v[152:153], v203 offset:25088
	v_mfma_f32_32x32x16_bf16 v[66:81], v[62:65], v[142:145], v[34:49]
	v_add_f32_e32 v50, v98, v99
	v_add_f32_e32 v50, v100, v50
	v_add_f32_e32 v50, v101, v50
	v_add_f32_e32 v50, v102, v50
	v_add_f32_e32 v50, v103, v50
	v_cvt_pk_bf16_f32 v138, v98, v99
	v_cvt_pk_bf16_f32 v139, v100, v101
	ds_read_b64_tr_b16 v[146:147], v203 offset:28672
	ds_read_b64_tr_b16 v[148:149], v203 offset:29184
	v_add_f32_e32 v50, v104, v50
	v_add_f32_e32 v50, v105, v50
	v_add_f32_e32 v50, v106, v50
	v_add_f32_e32 v114, v107, v50
	v_mfma_f32_32x32x16_bf16 v[50:65], v[174:177], v[142:145], v[34:49]
	v_cvt_pk_bf16_f32 v140, v102, v103
	v_cvt_pk_bf16_f32 v141, v104, v105
	ds_read_b64_tr_b16 v[98:99], v203 offset:25600
	ds_read_b64_tr_b16 v[100:101], v203 offset:26112
	v_mfma_f32_32x32x16_bf16 v[66:81], v[178:181], v[134:137], v[66:81]
	v_add_f32_e32 v102, v108, v114
	v_add_f32_e32 v102, v109, v102
	v_add_f32_e32 v102, v110, v102
	v_add_f32_e32 v114, v111, v102
	v_cvt_pk_bf16_f32 v130, v106, v107
	v_cvt_pk_bf16_f32 v131, v108, v109
	ds_read_b64_tr_b16 v[102:103], v203 offset:29696
	ds_read_b64_tr_b16 v[104:105], v203 offset:30208
	v_mfma_f32_32x32x16_bf16 v[50:65], v[170:173], v[134:137], v[50:65]
	v_add_f32_e32 v106, v112, v114
	v_add_f32_e32 v106, v113, v106
	v_add_f32_e32 v106, v82, v106
	v_add_f32_e32 v114, v83, v106
	v_cvt_pk_bf16_f32 v132, v110, v111
	v_cvt_pk_bf16_f32 v133, v112, v113
	ds_read_b64_tr_b16 v[106:107], v203 offset:26624
	ds_read_b64_tr_b16 v[108:109], v203 offset:27136
	v_mfma_f32_32x32x16_bf16 v[66:81], v[166:169], v[126:129], v[66:81]
	v_add_f32_e32 v110, v84, v114
	v_add_f32_e32 v110, v85, v110
	v_add_f32_e32 v110, v86, v110
	v_add_f32_e32 v110, v87, v110
	v_cvt_pk_bf16_f32 v122, v82, v83
	v_cvt_pk_bf16_f32 v123, v84, v85
	ds_read_b64_tr_b16 v[82:83], v203 offset:30720
	ds_read_b64_tr_b16 v[84:85], v203 offset:31232
	v_mfma_f32_32x32x16_bf16 v[50:65], v[162:165], v[126:129], v[50:65]
	v_add_f32_e32 v110, v88, v110
	v_add_f32_e32 v110, v89, v110
	v_add_f32_e32 v110, v90, v110
	v_add_f32_e32 v110, v91, v110
	v_cvt_pk_bf16_f32 v124, v86, v87
	v_cvt_pk_bf16_f32 v125, v88, v89
	ds_read_b64_tr_b16 v[86:87], v203 offset:27648
	ds_read_b64_tr_b16 v[88:89], v203 offset:28160
	v_mfma_f32_32x32x16_bf16 v[66:81], v[158:161], v[118:121], v[66:81]
	v_add_f32_e32 v110, v92, v110
	v_add_f32_e32 v110, v93, v110
	v_add_f32_e32 v110, v94, v110
	v_add_f32_e32 v110, v95, v110
	v_cvt_pk_bf16_f32 v114, v90, v91
	v_cvt_pk_bf16_f32 v115, v92, v93
	ds_read_b64_tr_b16 v[90:91], v203 offset:31744
	ds_read_b64_tr_b16 v[92:93], v203 offset:32256
	v_mfma_f32_32x32x16_bf16 v[50:65], v[154:157], v[118:121], v[50:65]
	v_add_f32_e32 v110, v96, v110
	v_add_f32_e32 v110, v97, v110
	v_cvt_pk_bf16_f32 v116, v94, v95
	s_add_i32 m0, s46, 0x2000
	v_cvt_pk_bf16_f32 v117, v96, v97
	global_load_lds_dwordx4 v189, s[100:101]
	s_add_i32 m0, s47, 0x4000
	v_add_f32_e32 v205, v190, v110
	global_load_lds_dwordx4 v187, s[100:101]

.Lf3_2_485:
	ds_read_b64_tr_b16 v[178:179], v203 offset:32768
	ds_read_b64_tr_b16 v[180:181], v203 offset:33280
	v_mfma_f32_32x32x16_bf16 v[98:113], v[174:177], v[142:145], v[34:49]
	v_add_f32_e32 v82, v66, v67
	v_add_f32_e32 v82, v68, v82
	v_add_f32_e32 v82, v69, v82
	v_add_f32_e32 v82, v70, v82
	v_add_f32_e32 v82, v71, v82
	v_cvt_pk_bf16_f32 v138, v66, v67
	v_cvt_pk_bf16_f32 v139, v68, v69
	ds_read_b64_tr_b16 v[174:175], v203 offset:36864
	ds_read_b64_tr_b16 v[176:177], v203 offset:37376
	v_add_f32_e32 v66, v72, v82
	v_mfma_f32_32x32x16_bf16 v[82:97], v[170:173], v[142:145], v[34:49]
	v_add_f32_e32 v66, v73, v66
	v_add_f32_e32 v66, v74, v66
	v_add_f32_e32 v114, v75, v66
	v_cvt_pk_bf16_f32 v140, v70, v71
	v_cvt_pk_bf16_f32 v141, v72, v73
	ds_read_b64_tr_b16 v[66:67], v203 offset:33792
	ds_read_b64_tr_b16 v[68:69], v203 offset:34304
	v_mfma_f32_32x32x16_bf16 v[98:113], v[166:169], v[134:137], v[98:113]
	v_add_f32_e32 v70, v76, v114
	v_add_f32_e32 v70, v77, v70
	v_add_f32_e32 v70, v78, v70
	v_add_f32_e32 v114, v79, v70
	v_cvt_pk_bf16_f32 v130, v74, v75
	v_cvt_pk_bf16_f32 v131, v76, v77
	ds_read_b64_tr_b16 v[70:71], v203 offset:37888
	ds_read_b64_tr_b16 v[72:73], v203 offset:38400
	v_mfma_f32_32x32x16_bf16 v[82:97], v[162:165], v[134:137], v[82:97]
	v_add_f32_e32 v74, v80, v114
	v_add_f32_e32 v74, v81, v74
	v_add_f32_e32 v74, v50, v74
	v_add_f32_e32 v114, v51, v74
	v_cvt_pk_bf16_f32 v132, v78, v79
	v_cvt_pk_bf16_f32 v133, v80, v81
	ds_read_b64_tr_b16 v[74:75], v203 offset:34816
	ds_read_b64_tr_b16 v[76:77], v203 offset:35328
	v_mfma_f32_32x32x16_bf16 v[98:113], v[158:161], v[126:129], v[98:113]
	v_add_f32_e32 v78, v52, v114
	v_add_f32_e32 v78, v53, v78
	v_add_f32_e32 v78, v54, v78
	v_add_f32_e32 v78, v55, v78
	v_cvt_pk_bf16_f32 v122, v50, v51
	v_cvt_pk_bf16_f32 v123, v52, v53
	ds_read_b64_tr_b16 v[50:51], v203 offset:38912
	ds_read_b64_tr_b16 v[52:53], v203 offset:39424
	v_mfma_f32_32x32x16_bf16 v[82:97], v[154:157], v[126:129], v[82:97]
	v_add_f32_e32 v78, v56, v78
	v_add_f32_e32 v78, v57, v78
	v_add_f32_e32 v78, v58, v78
	v_add_f32_e32 v78, v59, v78
	v_cvt_pk_bf16_f32 v124, v54, v55
	v_cvt_pk_bf16_f32 v125, v56, v57
	ds_read_b64_tr_b16 v[54:55], v203 offset:35840
	ds_read_b64_tr_b16 v[56:57], v203 offset:36352
	v_mfma_f32_32x32x16_bf16 v[98:113], v[150:153], v[118:121], v[98:113]
	v_add_f32_e32 v78, v60, v78
	v_add_f32_e32 v78, v61, v78
	v_add_f32_e32 v78, v62, v78
	v_add_f32_e32 v78, v63, v78
	v_cvt_pk_bf16_f32 v114, v58, v59
	v_cvt_pk_bf16_f32 v115, v60, v61
	ds_read_b64_tr_b16 v[58:59], v203 offset:39936
	ds_read_b64_tr_b16 v[60:61], v203 offset:40448
	v_mfma_f32_32x32x16_bf16 v[82:97], v[146:149], v[118:121], v[82:97]
	v_add_f32_e32 v78, v64, v78
	v_add_f32_e32 v78, v65, v78
	v_cvt_pk_bf16_f32 v116, v62, v63
	s_add_i32 m0, s46, 0x4000
	v_cvt_pk_bf16_f32 v117, v64, v65
	global_load_lds_dwordx4 v188, s[100:101]
	s_add_i32 m0, s47, 0x0
	v_add_f32_e32 v190, v205, v78
	global_load_lds_dwordx4 v186, s[100:101]

.Lf3_2_488:
	ds_read_b64_tr_b16 v[150:151], v203 offset:40960
	ds_read_b64_tr_b16 v[152:153], v203 offset:41472
	v_mfma_f32_32x32x16_bf16 v[66:81], v[62:65], v[142:145], v[34:49]
	v_add_f32_e32 v50, v98, v99
	v_add_f32_e32 v50, v100, v50
	v_add_f32_e32 v50, v101, v50
	v_add_f32_e32 v50, v102, v50
	v_add_f32_e32 v50, v103, v50
	v_cvt_pk_bf16_f32 v138, v98, v99
	v_cvt_pk_bf16_f32 v139, v100, v101
	ds_read_b64_tr_b16 v[146:147], v203 offset:45056
	ds_read_b64_tr_b16 v[148:149], v203 offset:45568
	v_add_f32_e32 v50, v104, v50
	v_add_f32_e32 v50, v105, v50
	v_add_f32_e32 v50, v106, v50
	v_add_f32_e32 v114, v107, v50
	v_mfma_f32_32x32x16_bf16 v[50:65], v[174:177], v[142:145], v[34:49]
	v_cvt_pk_bf16_f32 v140, v102, v103
	v_cvt_pk_bf16_f32 v141, v104, v105
	ds_read_b64_tr_b16 v[98:99], v203 offset:41984
	ds_read_b64_tr_b16 v[100:101], v203 offset:42496
	v_mfma_f32_32x32x16_bf16 v[66:81], v[178:181], v[134:137], v[66:81]
	v_add_f32_e32 v102, v108, v114
	v_add_f32_e32 v102, v109, v102
	v_add_f32_e32 v102, v110, v102
	v_add_f32_e32 v114, v111, v102
	v_cvt_pk_bf16_f32 v130, v106, v107
	v_cvt_pk_bf16_f32 v131, v108, v109
	ds_read_b64_tr_b16 v[102:103], v203 offset:46080
	ds_read_b64_tr_b16 v[104:105], v203 offset:46592
	v_mfma_f32_32x32x16_bf16 v[50:65], v[170:173], v[134:137], v[50:65]
	v_add_f32_e32 v106, v112, v114
	v_add_f32_e32 v106, v113, v106
	v_add_f32_e32 v106, v82, v106
	v_add_f32_e32 v114, v83, v106
	v_cvt_pk_bf16_f32 v132, v110, v111
	v_cvt_pk_bf16_f32 v133, v112, v113
	ds_read_b64_tr_b16 v[106:107], v203 offset:43008
	ds_read_b64_tr_b16 v[108:109], v203 offset:43520
	v_mfma_f32_32x32x16_bf16 v[66:81], v[166:169], v[126:129], v[66:81]
	v_add_f32_e32 v110, v84, v114
	v_add_f32_e32 v110, v85, v110
	v_add_f32_e32 v110, v86, v110
	v_add_f32_e32 v110, v87, v110
	v_cvt_pk_bf16_f32 v122, v82, v83
	v_cvt_pk_bf16_f32 v123, v84, v85
	ds_read_b64_tr_b16 v[82:83], v203 offset:47104
	ds_read_b64_tr_b16 v[84:85], v203 offset:47616
	v_mfma_f32_32x32x16_bf16 v[50:65], v[162:165], v[126:129], v[50:65]
	v_add_f32_e32 v110, v88, v110
	v_add_f32_e32 v110, v89, v110
	v_add_f32_e32 v110, v90, v110
	v_add_f32_e32 v110, v91, v110
	v_cvt_pk_bf16_f32 v124, v86, v87
	v_cvt_pk_bf16_f32 v125, v88, v89
	ds_read_b64_tr_b16 v[86:87], v203 offset:44032
	ds_read_b64_tr_b16 v[88:89], v203 offset:44544
	v_mfma_f32_32x32x16_bf16 v[66:81], v[158:161], v[118:121], v[66:81]
	v_add_f32_e32 v110, v92, v110
	v_add_f32_e32 v110, v93, v110
	v_add_f32_e32 v110, v94, v110
	v_add_f32_e32 v110, v95, v110
	v_cvt_pk_bf16_f32 v114, v90, v91
	v_cvt_pk_bf16_f32 v115, v92, v93
	ds_read_b64_tr_b16 v[90:91], v203 offset:48128
	ds_read_b64_tr_b16 v[92:93], v203 offset:48640
	v_mfma_f32_32x32x16_bf16 v[50:65], v[154:157], v[118:121], v[50:65]
	v_add_f32_e32 v110, v96, v110
	v_add_f32_e32 v110, v97, v110
	v_cvt_pk_bf16_f32 v116, v94, v95
	s_add_i32 m0, s46, 0x0
	v_cvt_pk_bf16_f32 v117, v96, v97
	global_load_lds_dwordx4 v189, s[100:101]
	s_add_i32 m0, s47, 0x2000
	v_add_f32_e32 v205, v190, v110
	global_load_lds_dwordx4 v187, s[100:101]
